# attention V pieces issued in scalar-base form (uniform base in SGPRs + 32-bit lane offset), no 64-bit VALU add per V piece
# baseline (speedup 1.0000x reference)
.LBB0_443:
	s_lshr_b32 s2, s15, 6
	s_ashr_i32 s78, s15, 8
	s_add_i32 s2, s2, s78
	s_and_b32 s10, s2, 3
	s_mul_i32 s3, s78, 23
	s_not_b32 s2, s10
	s_add_i32 s3, s3, s15
	s_lshl_b32 s4, s2, 1
	s_lshl_b32 s2, s78, 5
	s_and_b32 s48, s3, 63
	s_ashr_i32 s3, s2, 31
	s_lshl_b32 s34, s48, 7
	s_lshl_b64 s[2:3], s[2:3], 2
	s_add_u32 s2, s1, s2
	s_addc_u32 s3, s6, s3
	s_lshl_b32 s5, s10, 4
	v_mov_b32_e32 v0, s5
	global_load_dwordx4 v[2:5], v0, s[2:3]
	global_load_dwordx4 v[6:9], v0, s[2:3] offset:64
	v_cvt_f32_i32_e32 v0, s4
	s_ashr_i32 s79, s78, 31
	s_lshl_b64 s[2:3], s[78:79], 13
	v_or_b32_e32 v34, s34, v215
	v_or_b32_e32 v196, s2, v34
	v_mov_b32_e32 v197, s3
	v_lshlrev_b64 v[20:21], 12, v[196:197]
	s_lshl_b32 s57, s10, 7
	s_lshl_b32 s10, s10, 8
	v_lshl_add_u64 v[20:21], s[22:23], 0, v[20:21]
	v_lshl_add_u64 v[20:21], v[20:21], 0, s[10:11]
	s_mov_b32 s39, s11
	v_lshl_add_u64 v[20:21], v[20:21], 0, s[38:39]
	v_mov_b32_e32 v183, v153
	v_lshl_add_u64 v[20:21], v[20:21], 0, v[182:183]
	global_load_dwordx4 v[130:133], v[20:21], off
	global_load_dwordx4 v[134:137], v[20:21], off offset:32
	global_load_dwordx4 v[138:141], v[20:21], off offset:64
	global_load_dwordx4 v[142:145], v[20:21], off offset:96
	v_lshl_add_u64 v[24:25], s[2:3], 0, v[150:151]
	v_lshlrev_b64 v[24:25], 12, v[24:25]
	v_lshl_add_u64 v[24:25], s[22:23], 0, v[24:25]
	v_lshl_add_u64 v[24:25], v[24:25], 0, s[10:11]
	v_lshl_add_u64 v[202:203], v[24:25], 0, v[152:153]
	v_add_u32_e32 v22, s57, v216
	v_mov_b64_e32 v[24:25], s[28:29]
	v_mad_u64_u32 v[26:27], s[2:3], v22, s42, v[24:25]
	v_add_u32_e32 v22, s57, v217
	s_lshl_b64 s[2:3], s[78:79], 14
	v_mad_u64_u32 v[24:25], s[60:61], v22, s42, v[24:25]
	v_lshl_add_u64 v[26:27], v[26:27], 0, s[2:3]
	v_lshl_add_u64 v[24:25], v[24:25], 0, s[2:3]
	s_mul_i32 s90, s57, s42
	s_add_u32 s90, s28, s90
	s_addc_u32 s91, s29, 0
	s_add_u32 s90, s90, s2
	s_addc_u32 s91, s91, s3
	v_mov_b32_e32 v181, v153
	s_lshl_b32 s2, s34, 12
	s_mov_b32 s3, s11
	v_mov_b32_e32 v179, v153
	v_mad_u32_u24 v206, v217, s42, v180
	v_lshl_add_u64 v[24:25], v[202:203], 0, s[2:3]
	s_mov_b32 m0, s7
	v_mad_u32_u24 v204, v216, s42, v178
	v_lshl_add_u64 v[26:27], v[24:25], 0, s[30:31]
	s_add_i32 s3, s7, 0x2000
	s_or_b32 s2, s34, 64
	global_load_lds_dwordx4 v[26:27], off
	v_lshl_add_u64 v[24:25], v[24:25], 0, s[36:37]
	s_mov_b32 m0, s3
	s_lshl_b32 s60, s2, 12
	s_mov_b32 s61, s11
	global_load_lds_dwordx4 v[24:25], off
	v_lshl_add_u64 v[24:25], v[202:203], 0, s[60:61]
	v_lshl_add_u64 v[26:27], v[24:25], 0, s[30:31]
	s_mov_b32 m0, s43
	global_load_lds_dwordx4 v[26:27], off
	v_lshl_add_u64 v[24:25], v[24:25], 0, s[36:37]
	s_mov_b32 m0, s49
	s_lshl_b32 s62, s34, 1
	global_load_lds_dwordx4 v[24:25], off
	s_mov_b32 s63, s11
	s_add_u32 s92, s90, s62
	s_addc_u32 s93, s91, 0
	s_mov_b32 m0, s52
	s_nop 0
	global_load_lds_dwordx4 v204, s[92:93]
	s_mov_b32 m0, s53
	s_nop 0
	global_load_lds_dwordx4 v206, s[92:93]
	s_waitcnt vmcnt(11)
	v_mov_b32_e32 v10, v2
	s_waitcnt vmcnt(10)
	v_mov_b32_e32 v11, v6
	v_mov_b32_e32 v6, v3
	v_mov_b32_e32 v2, v4
	v_mov_b32_e32 v3, v8
	v_mov_b32_e32 v8, v5
	v_pk_add_f32 v[4:5], v[10:11], v[6:7]
	v_pk_add_f32 v[2:3], v[2:3], v[8:9]
	v_mul_f32_e32 v4, v4, v5
	v_mul_f32_e32 v2, v2, v3
	v_mul_f32_e32 v3, 0x4f800000, v4
	v_cmp_gt_f32_e32 vcc, s35, v4
	v_mul_f32_e32 v5, 0x4f800000, v2
	v_cmp_gt_f32_e64 s[2:3], s35, v2
	v_cndmask_b32_e32 v4, v4, v3, vcc
	v_sqrt_f32_e32 v6, v4
	v_cndmask_b32_e64 v2, v2, v5, s[2:3]
	v_sqrt_f32_e32 v5, v2
	v_exp_f32_e32 v3, v0
	v_add_u32_e32 v0, -1, v6
	v_fma_f32 v10, -v0, v6, v4
	v_add_u32_e32 v8, -1, v5
	v_add_u32_e32 v7, 1, v6
	v_fma_f32 v12, -v8, v5, v2
	v_cmp_ge_f32_e64 s[4:5], 0, v10
	v_add_u32_e32 v9, 1, v5
	v_fma_f32 v11, -v7, v6, v4
	v_cndmask_b32_e64 v0, v6, v0, s[4:5]
	v_cmp_ge_f32_e64 s[4:5], 0, v12
	v_fma_f32 v13, -v9, v5, v2
	s_nop 0
	v_cndmask_b32_e64 v5, v5, v8, s[4:5]
	v_cmp_lt_f32_e64 s[4:5], 0, v11
	s_nop 1
	v_cndmask_b32_e64 v0, v0, v7, s[4:5]
	v_cmp_lt_f32_e64 s[4:5], 0, v13
	v_mul_f32_e32 v6, 0x37800000, v0
	v_cndmask_b32_e32 v0, v0, v6, vcc
	v_cndmask_b32_e64 v5, v5, v9, s[4:5]
	v_mul_f32_e32 v7, 0x37800000, v5
	v_cmp_class_f32_e32 vcc, v4, v222
	v_cndmask_b32_e64 v5, v5, v7, s[2:3]
	s_nop 0
	v_cndmask_b32_e32 v0, v0, v4, vcc
	v_cmp_class_f32_e32 vcc, v2, v222
	s_nop 1
	v_cndmask_b32_e32 v2, v5, v2, vcc
	v_max3_f32 v0, v0, 0, v2
	v_mul_f32_e32 v2, 0x3f828f5c, v0
	v_cmp_gt_f32_e32 vcc, 0x42200000, v2
	s_cmp_lg_u64 vcc, 0
	s_cselect_b32 s98, 1, 0
	s_mov_b32 s99, 0
	v_pk_mul_f32 v[200:201], v[2:3], s[8:9]
	s_nop 0
	v_add_f32_e32 v0, 0x43220000, v200
	v_div_scale_f32 v2, s[2:3], v201, v201, v0
	v_rcp_f32_e32 v3, v2
	v_div_scale_f32 v4, vcc, v0, v201, v0
	s_mov_b32 s2, 0x46000000
	v_fma_f32 v5, -v2, v3, 1.0
	v_fmac_f32_e32 v3, v5, v3
	v_mul_f32_e32 v5, v4, v3
	v_fma_f32 v6, -v2, v5, v4
	v_fmac_f32_e32 v5, v6, v3
	v_fma_f32 v2, -v2, v5, v4
	v_div_fmas_f32 v2, v2, v3, v5
	v_div_fixup_f32 v0, v2, v201, v0
	v_cvt_i32_f32_e32 v2, v0
	v_cmp_gt_f32_e32 vcc, s2, v0
	v_readfirstlane_b32 s2, v2
	s_add_i32 s4, s2, 1
	s_and_b64 s[2:3], vcc, exec
	s_cselect_b32 s2, s4, 0x2000
	s_sub_i32 s3, s34, s2
	s_add_i32 s2, s2, s34
	s_addk_i32 s2, 0x7f
	s_max_i32 s3, s3, 0
	s_min_i32 s2, s2, 0x1fff
	s_lshr_b32 s33, s3, 6
	s_ashr_i32 s4, s2, 6
	s_sub_i32 s2, s4, s33
	s_bitcmp1_b32 s2, 0
	s_cselect_b64 s[2:3], -1, 0
	s_and_b64 vcc, exec, s[2:3]
	s_cbranch_vccnz .LBB0_449
	s_cmpk_gt_i32 s4, 0x7e
	s_mov_b64 s[2:3], -1
	s_cbranch_scc0 .LBB0_446
	s_add_i32 s5, s33, -1
	s_mov_b64 s[2:3], 0

.LBB0_449:
	s_lshl_b32 s2, s48, 1
	s_sub_i32 s39, s2, s33
	s_add_i32 s3, s7, 0x2000
	s_or_b32 s2, s34, 64
	s_lshl_b32 s60, s33, 6
	s_add_i32 s5, s60, 0x80
	s_cmp_gt_i32 s39, 0
	s_cselect_b32 s62, s60, s5
	s_ashr_i32 s63, s62, 31
	s_lshl_b64 s[62:63], s[62:63], 12
	v_lshl_add_u64 v[2:3], v[202:203], 0, s[62:63]
	v_lshl_add_u64 v[6:7], v[2:3], 0, s[30:31]
	s_mov_b32 m0, s50
	v_lshl_add_u64 v[2:3], v[2:3], 0, s[36:37]
	global_load_lds_dwordx4 v[6:7], off
	s_mov_b32 m0, s51
	v_add_u32_e32 v35, v218, v149
	global_load_lds_dwordx4 v[2:3], off
	s_waitcnt vmcnt(6) lgkmcnt(0)
	s_barrier
	ds_read_b128 v[18:21], v35
	ds_read_b128 v[36:39], v35 offset:4096
	v_and_b32_e32 v155, 0x7fffffff, v1
	v_mov_b32_e32 v0, v201
	v_pk_mul_f32 v[16:17], v[170:171], v[0:1] op_sel_hi:[1,0] neg_lo:[0,1] neg_hi:[0,1]
	v_pk_mul_f32 v[14:15], v[168:169], v[0:1] op_sel_hi:[1,0] neg_lo:[0,1] neg_hi:[0,1]
	v_pk_mul_f32 v[12:13], v[166:167], v[0:1] op_sel_hi:[1,0] neg_lo:[0,1] neg_hi:[0,1]
	v_pk_mul_f32 v[10:11], v[164:165], v[0:1] op_sel_hi:[1,0] neg_lo:[0,1] neg_hi:[0,1]
	v_pk_mul_f32 v[8:9], v[162:163], v[0:1] op_sel_hi:[1,0] neg_lo:[0,1] neg_hi:[0,1]
	v_pk_mul_f32 v[6:7], v[158:159], v[0:1] op_sel_hi:[1,0] neg_lo:[0,1] neg_hi:[0,1]
	v_pk_mul_f32 v[4:5], v[156:157], v[0:1] op_sel_hi:[1,0] neg_lo:[0,1] neg_hi:[0,1]
	v_pk_mul_f32 v[2:3], v[154:155], v[0:1] op_sel_hi:[1,0] neg_lo:[0,1] neg_hi:[0,1]
	v_pk_mul_f32 v[32:33], v[192:193], v[0:1] op_sel_hi:[1,0] neg_lo:[0,1] neg_hi:[0,1]
	v_pk_mul_f32 v[30:31], v[190:191], v[0:1] op_sel_hi:[1,0] neg_lo:[0,1] neg_hi:[0,1]
	s_waitcnt lgkmcnt(0)
	v_mfma_f32_32x32x16_bf16 v[2:17], v[18:21], v[130:133], v[2:17]
	v_mul_f32_e64 v28, v188, -v0
	v_mul_f32_e64 v29, v189, -v0
	v_mul_f32_e64 v26, v186, -v0
	v_mul_f32_e64 v27, v187, -v0
	v_mul_f32_e64 v24, v184, -v0
	v_mul_f32_e64 v25, v185, -v0
	v_pk_mul_f32 v[22:23], v[176:177], v[0:1] op_sel_hi:[1,0] neg_lo:[0,1] neg_hi:[0,1]
	v_pk_mul_f32 v[20:21], v[174:175], v[0:1] op_sel_hi:[1,0] neg_lo:[0,1] neg_hi:[0,1]
	v_pk_mul_f32 v[18:19], v[172:173], v[0:1] op_sel_hi:[1,0] neg_lo:[0,1] neg_hi:[0,1]
	v_add_u32_e32 v48, v218, v208
	v_add_u32_e32 v49, v218, v209
	v_mfma_f32_32x32x16_bf16 v[18:33], v[36:39], v[130:133], v[18:33]
	ds_read_b128 v[36:39], v48
	ds_read_b128 v[40:43], v48 offset:4096
	v_add_u32_e32 v50, v218, v226
	s_sub_i32 s48, s4, s33
	s_cmp_gt_i32 s39, 1
	s_cselect_b32 s4, 1, 3
	s_add_i32 s4, s4, s33
	s_lshl_b32 s4, s4, 6
	s_waitcnt lgkmcnt(1)
	v_mfma_f32_32x32x16_bf16 v[2:17], v[36:39], v[134:137], v[2:17]
	s_ashr_i32 s5, s4, 31
	s_lshl_b64 s[4:5], s[4:5], 12
	s_mov_b32 m0, s7
	s_mov_b32 s10, 0
	s_waitcnt lgkmcnt(0)
	v_mfma_f32_32x32x16_bf16 v[18:33], v[40:43], v[134:137], v[18:33]
	ds_read_b128 v[36:39], v49
	ds_read_b128 v[40:43], v49 offset:4096
	s_waitcnt lgkmcnt(1)
	v_mfma_f32_32x32x16_bf16 v[2:17], v[36:39], v[138:141], v[2:17]
	ds_read_b128 v[36:39], v50
	s_waitcnt lgkmcnt(1)
	v_mfma_f32_32x32x16_bf16 v[18:33], v[40:43], v[138:141], v[18:33]
	ds_read_b128 v[40:43], v50 offset:4096
	s_waitcnt vmcnt(4) lgkmcnt(0)
	s_barrier
	s_waitcnt lgkmcnt(1)
	v_mfma_f32_32x32x16_bf16 v[2:17], v[36:39], v[142:145], v[2:17]
	v_lshl_add_u64 v[36:37], v[202:203], 0, s[4:5]
	v_lshl_add_u64 v[38:39], v[36:37], 0, s[30:31]
	global_load_lds_dwordx4 v[38:39], off
	v_lshl_add_u64 v[36:37], v[36:37], 0, s[36:37]
	s_mov_b32 m0, s3
	v_or_b32_e32 v38, s2, v148
	global_load_lds_dwordx4 v[36:37], off
	s_add_u32 s92, s92, 0x80
	s_addc_u32 s93, s93, 0
	s_mov_b32 m0, s54
	s_waitcnt lgkmcnt(0)
	v_mfma_f32_32x32x16_bf16 v[18:33], v[40:43], v[142:145], v[18:33]
	global_load_lds_dwordx4 v204, s[92:93]
	s_mov_b32 m0, s55
	s_nop 0
	global_load_lds_dwordx4 v206, s[92:93]
	v_max3_f32 v36, v2, v3, v18
	v_max3_f32 v37, v4, v5, v19
	s_nop 15
	s_nop 15
	s_nop 15
	s_nop 0
	v_max3_f32 v36, v36, v20, v21
	v_max3_f32 v37, v37, v8, v9
	s_nop 0
	v_max3_f32 v36, v36, v6, v7
	v_max3_f32 v37, v37, v24, v25
	s_nop 0
	v_max3_f32 v36, v36, v22, v23
	v_max3_f32 v37, v37, v12, v13
	s_nop 0
	v_max3_f32 v36, v36, v10, v11
	v_max3_f32 v37, v37, v28, v29
	s_nop 0
	v_max3_f32 v36, v36, v26, v27
	v_max3_f32 v37, v37, v16, v17
	s_nop 0
	v_max3_f32 v36, v36, v14, v15
	v_max3_f32 v37, v37, v32, v33
	s_nop 0
	v_max3_f32 v36, v36, v30, v31
	s_nop 0
	v_max_f32_e32 v36, v36, v37
	s_nop 0
	v_mov_b32_e32 v37, v36
	s_nop 1
	v_permlane32_swap_b32 v36, v37
	s_nop 1
	s_nop 0
	v_max_f32_e32 v37, v37, v37
	v_max_f32_e32 v36, v36, v36
	v_max_f32_e32 v37, v36, v37
	v_sub_f32_e32 v2, v2, v37
	v_sub_f32_e32 v18, v18, v37
	v_sub_f32_e32 v3, v3, v37
	v_sub_f32_e32 v19, v19, v37
	v_sub_f32_e32 v4, v4, v37
	v_sub_f32_e32 v20, v20, v37
	v_sub_f32_e32 v5, v5, v37
	v_sub_f32_e32 v21, v21, v37
	v_sub_f32_e32 v6, v6, v37
	v_sub_f32_e32 v22, v22, v37
	v_sub_f32_e32 v7, v7, v37
	v_sub_f32_e32 v23, v23, v37
	v_sub_f32_e32 v8, v8, v37
	v_sub_f32_e32 v24, v24, v37
	v_sub_f32_e32 v9, v9, v37
	v_sub_f32_e32 v25, v25, v37
	v_sub_f32_e32 v10, v10, v37
	v_sub_f32_e32 v26, v26, v37
	v_sub_f32_e32 v11, v11, v37
	v_sub_f32_e32 v27, v27, v37
	v_sub_f32_e32 v12, v12, v37
	v_sub_f32_e32 v28, v28, v37
	v_sub_f32_e32 v13, v13, v37
	v_sub_f32_e32 v29, v29, v37
	v_sub_f32_e32 v14, v14, v37
	v_sub_f32_e32 v30, v30, v37
	v_sub_f32_e32 v15, v15, v37
	v_sub_f32_e32 v31, v31, v37
	v_sub_f32_e32 v16, v16, v37
	v_sub_f32_e32 v32, v32, v37
	v_sub_f32_e32 v17, v17, v37
	v_sub_f32_e32 v33, v33, v37
	v_exp_f32_e32 v52, v2
	v_exp_f32_e32 v53, v18
	v_exp_f32_e32 v54, v3
	v_exp_f32_e32 v55, v19
	v_exp_f32_e32 v56, v4
	v_exp_f32_e32 v57, v20
	v_exp_f32_e32 v58, v5
	v_exp_f32_e32 v59, v21
	v_exp_f32_e32 v60, v6
	v_exp_f32_e32 v61, v22
	v_exp_f32_e32 v62, v7
	v_exp_f32_e32 v63, v23
	v_exp_f32_e32 v64, v8
	v_exp_f32_e32 v65, v24
	v_exp_f32_e32 v101, v9
	v_exp_f32_e32 v102, v25
	v_exp_f32_e32 v103, v10
	v_exp_f32_e32 v104, v26
	v_exp_f32_e32 v114, v27
	v_exp_f32_e32 v105, v11
	v_exp_f32_e32 v107, v12
	v_exp_f32_e32 v115, v28
	v_exp_f32_e32 v108, v13
	v_exp_f32_e32 v116, v29
	v_exp_f32_e32 v109, v14
	v_exp_f32_e32 v117, v30
	ds_read_b128 v[10:13], v35 offset:16384
	v_exp_f32_e32 v118, v15
	v_exp_f32_e32 v119, v31
	ds_read_b128 v[2:5], v35 offset:20480
	v_exp_f32_e32 v35, v16
	v_exp_f32_e32 v120, v32
	ds_read_b128 v[6:9], v48 offset:16384
	v_exp_f32_e32 v121, v17
	v_exp_f32_e32 v122, v33
	ds_read_b128 v[14:17], v48 offset:20480
	ds_read_b128 v[18:21], v49 offset:16384
	ds_read_b128 v[22:25], v49 offset:20480
	ds_read_b128 v[26:29], v50 offset:16384
	ds_read_b128 v[30:33], v50 offset:20480
	v_add_f32_e32 v36, 0, v52
	v_add_f32_e32 v36, v53, v36
	v_add_f32_e32 v36, v54, v36
	v_add_f32_e32 v36, v55, v36
	v_add_f32_e32 v36, v56, v36
	v_add_f32_e32 v36, v57, v36
	v_add_f32_e32 v36, v58, v36
	v_add_f32_e32 v36, v59, v36
	v_add_f32_e32 v36, v60, v36
	v_add_f32_e32 v36, v61, v36
	v_add_f32_e32 v36, v62, v36
	v_add_f32_e32 v36, v63, v36
	v_add_f32_e32 v36, v64, v36
	v_add_f32_e32 v36, v65, v36
	v_add_f32_e32 v36, v101, v36
	v_add_f32_e32 v36, v102, v36
	v_add_f32_e32 v36, v103, v36
	v_add_f32_e32 v36, v104, v36
	v_add_f32_e32 v36, v105, v36
	v_add_f32_e32 v36, v114, v36
	v_add_f32_e32 v36, v107, v36
	v_add_f32_e32 v36, v115, v36
	v_add_f32_e32 v36, v108, v36
	v_add_f32_e32 v36, v116, v36
	v_add_f32_e32 v36, v109, v36
	v_add_f32_e32 v36, v117, v36
	v_add_f32_e32 v36, v118, v36
	v_add_f32_e32 v36, v119, v36
	v_add_f32_e32 v36, v35, v36
	v_add_f32_e32 v36, v120, v36
	v_add_f32_e32 v36, v121, v36
	v_add_f32_e32 v36, v122, v36
	v_sub_u32_e32 v82, v34, v38
	v_pk_add_f32 v[198:199], v[36:37], 0 op_sel_hi:[1,0]
	v_add_u32_e32 v36, -1, v82
	v_add_u32_e32 v37, -3, v82
	v_add_u32_e32 v38, -2, v82
	v_add_u32_e32 v39, -5, v82
	v_add_u32_e32 v40, -4, v82
	v_add_u32_e32 v41, -7, v82
	v_add_u32_e32 v42, -6, v82
	v_subrev_u32_e32 v43, 17, v82
	v_add_u32_e32 v44, -16, v82
	v_subrev_u32_e32 v45, 19, v82
	v_subrev_u32_e32 v46, 18, v82
	v_subrev_u32_e32 v47, 21, v82
	v_subrev_u32_e32 v48, 20, v82
	v_subrev_u32_e32 v49, 23, v82
	v_subrev_u32_e32 v50, 22, v82
	v_cvt_f32_i32_e32 v50, v50
	v_cvt_f32_i32_e32 v51, v49
	v_cvt_f32_i32_e32 v48, v48
	v_cvt_f32_i32_e32 v49, v47
	v_cvt_f32_i32_e32 v46, v46
	v_cvt_f32_i32_e32 v47, v45
	v_cvt_f32_i32_e32 v44, v44
	v_cvt_f32_i32_e32 v45, v43
	v_cvt_f32_i32_e32 v42, v42
	v_cvt_f32_i32_e32 v43, v41
	v_cvt_f32_i32_e32 v40, v40
	v_cvt_f32_i32_e32 v41, v39
	v_cvt_f32_i32_e32 v39, v82
	v_cvt_f32_i32_e32 v66, v36
	v_cvt_f32_i32_e32 v67, v37
	v_cvt_f32_i32_e32 v38, v38
	v_and_b32_e32 v36, 0x7fffffff, v39
	v_and_b32_e32 v37, 0x7fffffff, v66
	v_and_b32_e32 v39, 0x7fffffff, v67
	v_and_b32_e32 v38, 0x7fffffff, v38
	v_and_b32_e32 v41, 0x7fffffff, v41
	v_and_b32_e32 v40, 0x7fffffff, v40
	v_and_b32_e32 v43, 0x7fffffff, v43
	v_and_b32_e32 v42, 0x7fffffff, v42
	v_and_b32_e32 v45, 0x7fffffff, v45
	v_and_b32_e32 v44, 0x7fffffff, v44
	v_and_b32_e32 v47, 0x7fffffff, v47
	v_and_b32_e32 v46, 0x7fffffff, v46
	v_and_b32_e32 v49, 0x7fffffff, v49
	v_and_b32_e32 v48, 0x7fffffff, v48
	v_and_b32_e32 v51, 0x7fffffff, v51
	v_and_b32_e32 v50, 0x7fffffff, v50
	v_pk_fma_f32 v[80:81], v[0:1], v[50:51], v[198:199] op_sel:[0,0,1] op_sel_hi:[0,1,1] neg_lo:[1,0,1] neg_hi:[1,0,1]
	v_pk_fma_f32 v[78:79], v[0:1], v[48:49], v[198:199] op_sel:[0,0,1] op_sel_hi:[0,1,1] neg_lo:[1,0,1] neg_hi:[1,0,1]
	v_pk_fma_f32 v[76:77], v[0:1], v[46:47], v[198:199] op_sel:[0,0,1] op_sel_hi:[0,1,1] neg_lo:[1,0,1] neg_hi:[1,0,1]
	v_pk_fma_f32 v[74:75], v[0:1], v[44:45], v[198:199] op_sel:[0,0,1] op_sel_hi:[0,1,1] neg_lo:[1,0,1] neg_hi:[1,0,1]
	v_pk_fma_f32 v[72:73], v[0:1], v[42:43], v[198:199] op_sel:[0,0,1] op_sel_hi:[0,1,1] neg_lo:[1,0,1] neg_hi:[1,0,1]
	v_pk_fma_f32 v[70:71], v[0:1], v[40:41], v[198:199] op_sel:[0,0,1] op_sel_hi:[0,1,1] neg_lo:[1,0,1] neg_hi:[1,0,1]
	v_pk_fma_f32 v[68:69], v[0:1], v[38:39], v[198:199] op_sel:[0,0,1] op_sel_hi:[0,1,1] neg_lo:[1,0,1] neg_hi:[1,0,1]
	v_pk_fma_f32 v[66:67], v[0:1], v[36:37], v[198:199] op_sel:[0,0,1] op_sel_hi:[0,1,1] neg_lo:[1,0,1] neg_hi:[1,0,1]
	v_subrev_u32_e32 v36, 33, v82
	v_subrev_u32_e32 v37, 32, v82
	v_subrev_u32_e32 v38, 35, v82
	v_subrev_u32_e32 v39, 34, v82
	v_subrev_u32_e32 v40, 37, v82
	v_subrev_u32_e32 v41, 36, v82
	v_subrev_u32_e32 v42, 39, v82
	v_subrev_u32_e32 v43, 38, v82
	v_subrev_u32_e32 v44, 49, v82
	v_subrev_u32_e32 v45, 48, v82
	v_subrev_u32_e32 v46, 51, v82
	v_subrev_u32_e32 v47, 50, v82
	v_subrev_u32_e32 v48, 53, v82
	v_subrev_u32_e32 v49, 52, v82
	v_subrev_u32_e32 v50, 55, v82
	v_subrev_u32_e32 v51, 54, v82
	v_cvt_f32_i32_e32 v82, v51
	v_cvt_f32_i32_e32 v50, v50
	v_cvt_f32_i32_e32 v51, v49
	v_cvt_f32_i32_e32 v48, v48
	v_cvt_f32_i32_e32 v49, v47
	v_cvt_f32_i32_e32 v46, v46
	v_cvt_f32_i32_e32 v47, v45
	v_cvt_f32_i32_e32 v44, v44
	v_cvt_f32_i32_e32 v45, v43
	v_cvt_f32_i32_e32 v42, v42
	v_cvt_f32_i32_e32 v43, v41
	v_cvt_f32_i32_e32 v40, v40
	v_cvt_f32_i32_e32 v36, v36
	v_cvt_f32_i32_e32 v41, v37
	v_cvt_f32_i32_e32 v38, v38
	v_cvt_f32_i32_e32 v83, v39
	v_and_b32_e32 v37, 0x7fffffff, v36
	v_and_b32_e32 v36, 0x7fffffff, v41
	v_and_b32_e32 v39, 0x7fffffff, v38
	v_and_b32_e32 v38, 0x7fffffff, v83
	v_and_b32_e32 v41, 0x7fffffff, v40
	v_and_b32_e32 v40, 0x7fffffff, v43
	v_and_b32_e32 v43, 0x7fffffff, v42
	v_and_b32_e32 v42, 0x7fffffff, v45
	v_and_b32_e32 v45, 0x7fffffff, v44
	v_and_b32_e32 v44, 0x7fffffff, v47
	v_and_b32_e32 v47, 0x7fffffff, v46
	v_and_b32_e32 v46, 0x7fffffff, v49
	v_and_b32_e32 v49, 0x7fffffff, v48
	v_and_b32_e32 v48, 0x7fffffff, v51
	v_and_b32_e32 v51, 0x7fffffff, v50
	v_and_b32_e32 v50, 0x7fffffff, v82
	v_pk_fma_f32 v[96:97], v[0:1], v[50:51], v[198:199] op_sel:[0,0,1] op_sel_hi:[0,1,1] neg_lo:[1,0,1] neg_hi:[1,0,1]
	v_pk_fma_f32 v[94:95], v[0:1], v[48:49], v[198:199] op_sel:[0,0,1] op_sel_hi:[0,1,1] neg_lo:[1,0,1] neg_hi:[1,0,1]
	v_pk_fma_f32 v[92:93], v[0:1], v[46:47], v[198:199] op_sel:[0,0,1] op_sel_hi:[0,1,1] neg_lo:[1,0,1] neg_hi:[1,0,1]
	v_pk_fma_f32 v[90:91], v[0:1], v[44:45], v[198:199] op_sel:[0,0,1] op_sel_hi:[0,1,1] neg_lo:[1,0,1] neg_hi:[1,0,1]
	v_pk_fma_f32 v[88:89], v[0:1], v[42:43], v[198:199] op_sel:[0,0,1] op_sel_hi:[0,1,1] neg_lo:[1,0,1] neg_hi:[1,0,1]
	v_pk_fma_f32 v[86:87], v[0:1], v[40:41], v[198:199] op_sel:[0,0,1] op_sel_hi:[0,1,1] neg_lo:[1,0,1] neg_hi:[1,0,1]
	v_pk_fma_f32 v[84:85], v[0:1], v[38:39], v[198:199] op_sel:[0,0,1] op_sel_hi:[0,1,1] neg_lo:[1,0,1] neg_hi:[1,0,1]
	v_pk_fma_f32 v[82:83], v[0:1], v[36:37], v[198:199] op_sel:[0,0,1] op_sel_hi:[0,1,1] neg_lo:[1,0,1] neg_hi:[1,0,1]
	s_waitcnt lgkmcnt(0)
	v_mfma_f32_32x32x16_bf16 v[66:81], v[10:13], v[130:133], v[66:81]
	v_cvt_pk_bf16_f32 v98, v52, v54
	v_cvt_pk_bf16_f32 v99, v56, v58
	v_cvt_pk_bf16_f32 v100, v60, v62
	v_cvt_pk_bf16_f32 v101, v64, v101
	v_cvt_pk_bf16_f32 v110, v53, v55
	v_cvt_pk_bf16_f32 v111, v57, v59
	v_cvt_pk_bf16_f32 v112, v61, v63
	v_mfma_f32_32x32x16_bf16 v[82:97], v[2:5], v[130:133], v[82:97]
	v_cvt_pk_bf16_f32 v113, v65, v102
	v_cvt_pk_bf16_f32 v106, v103, v105
	v_cvt_pk_bf16_f32 v107, v107, v108
	v_cvt_pk_bf16_f32 v108, v109, v118
	v_cvt_pk_bf16_f32 v109, v35, v121
	v_cvt_pk_bf16_f32 v114, v104, v114
	v_cvt_pk_bf16_f32 v115, v115, v116
	v_mfma_f32_32x32x16_bf16 v[66:81], v[6:9], v[134:137], v[66:81]
	v_cvt_pk_bf16_f32 v116, v117, v119
	s_cmp_lt_i32 s48, 2
	v_cvt_pk_bf16_f32 v117, v120, v122
	v_mfma_f32_32x32x16_bf16 v[82:97], v[14:17], v[134:137], v[82:97]
	v_mfma_f32_32x32x16_bf16 v[66:81], v[18:21], v[138:141], v[66:81]
	v_mfma_f32_32x32x16_bf16 v[82:97], v[22:25], v[138:141], v[82:97]
	v_mfma_f32_32x32x16_bf16 v[66:81], v[26:29], v[142:145], v[66:81]
	v_mfma_f32_32x32x16_bf16 v[82:97], v[30:33], v[142:145], v[82:97]
	s_cbranch_scc1 .LBB0_472
	v_sub_u32_e32 v0, v148, v34
	v_cvt_f32_i32_e32 v155, v0
	v_mov_b32_e32 v16, v153
	v_mov_b32_e32 v17, v153
	v_mov_b32_e32 v2, v153
	v_mov_b32_e32 v3, v153
	v_mov_b32_e32 v4, v153
	v_mov_b32_e32 v5, v153
	v_mov_b32_e32 v6, v153
	v_mov_b32_e32 v7, v153
	v_mov_b32_e32 v8, v153
	v_mov_b32_e32 v9, v153
	v_mov_b32_e32 v10, v153
	v_mov_b32_e32 v11, v153
	v_mov_b32_e32 v12, v153
	v_mov_b32_e32 v13, v153
	v_mov_b32_e32 v14, v153
	v_mov_b32_e32 v15, v153
	v_mov_b64_e32 v[32:33], v[16:17]
	v_mov_b64_e32 v[48:49], v[16:17]
	v_mov_b64_e32 v[64:65], v[16:17]
	s_mov_b64 s[2:3], 0
	v_mov_b32_e32 v0, 1.0
	s_mov_b32 s62, 2
	s_mov_b32 s34, 5
	v_mov_b64_e32 v[30:31], v[14:15]
	v_mov_b64_e32 v[28:29], v[12:13]
	v_mov_b64_e32 v[26:27], v[10:11]
	v_mov_b64_e32 v[24:25], v[8:9]
	v_mov_b64_e32 v[22:23], v[6:7]
	v_mov_b64_e32 v[20:21], v[4:5]
	v_mov_b64_e32 v[18:19], v[2:3]
	v_mov_b64_e32 v[46:47], v[14:15]
	v_mov_b64_e32 v[44:45], v[12:13]
	v_mov_b64_e32 v[42:43], v[10:11]
	v_mov_b64_e32 v[40:41], v[8:9]
	v_mov_b64_e32 v[38:39], v[6:7]
	v_mov_b64_e32 v[36:37], v[4:5]
	v_mov_b64_e32 v[34:35], v[2:3]
	v_mov_b64_e32 v[62:63], v[14:15]
	v_mov_b64_e32 v[60:61], v[12:13]
	v_mov_b64_e32 v[58:59], v[10:11]
	v_mov_b64_e32 v[56:57], v[8:9]
	v_mov_b64_e32 v[54:55], v[6:7]
	v_mov_b64_e32 v[52:53], v[4:5]
	v_mov_b64_e32 v[50:51], v[2:3]
	s_mov_b32 s81, 0
	s_mov_b32 s83, 0
	s_mov_b32 s85, 0
	s_add_i32 s61, s34, -2
	s_cmp_gt_i32 s61, s48
	s_mov_b64 s[4:5], -1
	s_cbranch_scc0 .LBB0_468

.LBB0_458:
	s_add_i32 s78, s34, -4
	s_cmp_gt_i32 s78, s39
	s_cselect_b64 vcc, -1, 0
	s_cselect_b32 s82, s63, s60
	v_cndmask_b32_e64 v200, v201, -v201, vcc
	s_lshl_b32 s84, s82, 1
	s_add_u32 s92, s90, s84
	s_addc_u32 s93, s91, 0
	s_addk_i32 s80, 0xc000
	s_cmp_lg_u32 s10, 0
	s_cselect_b32 s80, s80, 0x8000
	s_add_i32 s80, s14, s80
	s_add_i32 m0, s80, 0xc000
	v_cvt_f32_i32_e32 v98, s82
	global_load_lds_dwordx4 v204, s[92:93]
	s_add_i32 m0, s80, 0xc400
	s_nop 0
	global_load_lds_dwordx4 v206, s[92:93]
	v_add_u32_e32 v183, s79, v218
	v_add_f32_e32 v98, v155, v98
	v_fma_f32 v224, v200, v98, -v199
	v_fma_f32 v98, 0, v200, v224
	v_add_f32_e32 v99, v200, v224
	v_fma_f32 v100, v200, s64, v224
	v_fma_f32 v101, v200, s65, v224
	v_fma_f32 v102, v200, s66, v224
	v_fma_f32 v103, v200, s67, v224
	v_mul_f32_e32 v240, 0x42000000, v200
	ds_read_b128 v[228:231], v181 offset:53248
	s_waitcnt lgkmcnt(2)
	v_mfma_f32_32x32x16_bf16 v[18:33], v[126:129], v[106:109], v[18:33]
	v_add_f32_e32 v254, v70, v254
	v_add_f32_e32 v255, v252, v255
	v_exp_f32_e32 v71, v71
	v_fma_f32 v104, v200, s68, v224
	v_fma_f32 v105, v200, s69, v224
	ds_read_b128 v[126:129], v181 offset:57344
	v_mfma_f32_32x32x16_bf16 v[2:17], v[118:121], v[106:109], v[2:17]
	s_setprio 0
	v_add_f32_e32 v254, v71, v254
	v_exp_f32_e32 v253, v87
	v_exp_f32_e32 v82, v72
	ds_read_b128 v[118:121], v181 offset:61440
	s_waitcnt lgkmcnt(2)
	v_mfma_f32_32x32x16_bf16 v[50:65], v[122:125], v[110:113], v[50:65]
	v_add_f32_e32 v255, v253, v255
	v_add_f32_e32 v254, v82, v254
	v_exp_f32_e32 v72, v88
	v_fma_f32 v106, v200, s70, v224
	v_fma_f32 v107, v200, s71, v224
	v_add_u32_e32 v179, v179, v226
	ds_read_b128 v[122:125], v179 offset:49152
	v_mfma_f32_32x32x16_bf16 v[34:49], v[228:231], v[110:113], v[34:49]
	v_add_f32_e32 v255, v72, v255
	v_exp_f32_e32 v83, v73
	v_exp_f32_e32 v73, v89
	ds_read_b128 v[228:231], v179 offset:53248
	s_waitcnt lgkmcnt(2)
	v_mfma_f32_32x32x16_bf16 v[18:33], v[126:129], v[110:113], v[18:33]
	v_add_f32_e32 v254, v83, v254
	v_add_f32_e32 v255, v73, v255
	v_exp_f32_e32 v74, v74
	v_fma_f32 v108, v200, s72, v224
	v_fma_f32 v109, v200, s73, v224
	ds_read_b128 v[126:129], v179 offset:57344
	v_mfma_f32_32x32x16_bf16 v[2:17], v[118:121], v[110:113], v[2:17]
	v_add_f32_e32 v254, v74, v254
	v_exp_f32_e32 v90, v90
	v_exp_f32_e32 v75, v75
	ds_read_b128 v[118:121], v179 offset:61440
	s_waitcnt lgkmcnt(2)
	v_mfma_f32_32x32x16_bf16 v[50:65], v[122:125], v[114:117], v[50:65]
	v_add_f32_e32 v255, v90, v255
	v_add_f32_e32 v254, v75, v254
	v_exp_f32_e32 v91, v91
	v_fma_f32 v110, v200, s74, v224
	v_fma_f32 v111, v200, s75, v224
	v_add_u32_e32 v112, v183, v149
	ds_read_b128 v[232:235], v112
	v_mfma_f32_32x32x16_bf16 v[34:49], v[228:231], v[114:117], v[34:49]
	v_add_f32_e32 v255, v91, v255
	v_exp_f32_e32 v76, v76
	v_exp_f32_e32 v92, v92
	ds_read_b128 v[228:231], v112 offset:4096
	s_waitcnt lgkmcnt(2)
	v_mfma_f32_32x32x16_bf16 v[18:33], v[126:129], v[114:117], v[18:33]
	v_add_f32_e32 v254, v76, v254
	v_add_f32_e32 v255, v92, v255
	v_exp_f32_e32 v77, v77
	v_fma_f32 v112, v200, s76, v224
	v_fma_f32 v113, v200, s77, v224
	v_add_u32_e32 v179, v183, v208
	ds_read_b128 v[236:239], v179
	v_mfma_f32_32x32x16_bf16 v[2:17], v[118:121], v[114:117], v[2:17]
	v_add_f32_e64 v114, v240, v98
	v_add_f32_e64 v115, v240, v99
	v_add_f32_e64 v128, v240, v112
	v_add_f32_e64 v129, v240, v113
	v_add_f32_e64 v126, v240, v110
	v_add_f32_e64 v127, v240, v111
	v_add_f32_e32 v124, v240, v108
	v_add_f32_e32 v125, v240, v109
	v_add_f32_e32 v122, v240, v106
	v_add_f32_e32 v123, v240, v107
	v_add_f32_e32 v120, v240, v104
	v_add_f32_e32 v121, v240, v105
	v_add_f32_e32 v118, v240, v102
	v_add_f32_e32 v119, v240, v103
	v_add_f32_e32 v116, v240, v100
	v_add_f32_e32 v117, v240, v101
	ds_read_b128 v[240:243], v179 offset:4096
	s_waitcnt lgkmcnt(2)
	v_mfma_f32_32x32x16_bf16 v[98:113], v[232:235], v[130:133], v[98:113]
	v_add_f32_e32 v254, v77, v254
	v_exp_f32_e32 v93, v93
	v_exp_f32_e32 v78, v78
	v_add_u32_e32 v179, v183, v209
	ds_read_b128 v[232:235], v179
	v_mfma_f32_32x32x16_bf16 v[114:129], v[228:231], v[130:133], v[114:129]
	v_add_f32_e32 v255, v93, v255
	v_add_f32_e32 v254, v78, v254
	v_exp_f32_e32 v94, v94
	v_exp_f32_e32 v79, v79
	ds_read_b128 v[228:231], v179 offset:4096
	s_waitcnt lgkmcnt(2)
	v_mfma_f32_32x32x16_bf16 v[98:113], v[236:239], v[134:137], v[98:113]
	v_add_f32_e32 v255, v94, v255
	v_add_f32_e32 v254, v79, v254
	v_exp_f32_e32 v95, v95
	v_exp_f32_e32 v80, v80
	v_add_u32_e32 v179, v183, v226
	ds_read_b128 v[236:239], v179
	v_mfma_f32_32x32x16_bf16 v[114:129], v[240:243], v[134:137], v[114:129]
	v_add_f32_e32 v255, v95, v255
	v_add_f32_e32 v254, v80, v254
	v_exp_f32_e32 v96, v96
	v_exp_f32_e32 v81, v81
	ds_read_b128 v[240:243], v179 offset:4096
	s_waitcnt lgkmcnt(2)
	v_mfma_f32_32x32x16_bf16 v[98:113], v[232:235], v[138:141], v[98:113]
	v_add_f32_e32 v255, v96, v255
	v_add_f32_e32 v254, v81, v254
	v_exp_f32_e32 v97, v97
	v_mfma_f32_32x32x16_bf16 v[114:129], v[228:231], v[138:141], v[114:129]
	v_add_f32_e32 v255, v97, v255
	v_add_f32_e32 v254, v255, v254
	s_waitcnt lgkmcnt(0)
	v_mfma_f32_32x32x16_bf16 v[98:113], v[236:239], v[142:145], v[98:113]
	v_mfma_f32_32x32x16_bf16 v[114:129], v[240:243], v[142:145], v[114:129]
	s_cmp_lg_u32 s4, 0
	s_cbranch_scc0 .LBB0_471
	s_waitcnt vmcnt(4) lgkmcnt(0)
	s_barrier
	s_cmp_eq_u32 s100, 0
	s_cbranch_scc1 .Lattn_fair_a
	s_setprio 1

.LBB0_466:
	s_cmp_lt_i32 s78, s39
	s_cselect_b64 vcc, -1, 0
	s_cselect_b32 s60, s78, s61
	v_cndmask_b32_e64 v228, -v201, v201, vcc
	s_add_i32 s60, s60, s33
	s_lshl_b32 s78, s60, 6
	s_lshl_b32 s80, s78, 1
	s_add_u32 s92, s90, s80
	s_addc_u32 s93, s91, 0
	s_addk_i32 s62, 0xc000
	s_cmp_lg_u32 s5, 0
	s_cselect_b32 s60, s62, 0x8000
	s_add_i32 s60, s14, s60
	s_add_i32 m0, s60, 0xc000
	v_cvt_f32_i32_e32 v66, s78
	global_load_lds_dwordx4 v204, s[92:93]
	s_add_i32 m0, s60, 0xc400
	s_nop 0
	global_load_lds_dwordx4 v206, s[92:93]
	v_exp_f32_e32 v231, v98
	v_add_f32_e32 v66, v155, v66
	v_fma_f32 v230, v228, v66, -v199
	v_add_u32_e32 v229, s10, v218
	v_exp_f32_e32 v233, v114
	v_fma_f32 v66, 0, v228, v230
	v_exp_f32_e32 v234, v99
	v_exp_f32_e32 v235, v115
	v_add_f32_e32 v67, v228, v230
	v_exp_f32_e32 v236, v100
	v_exp_f32_e32 v237, v116
	v_exp_f32_e32 v238, v101
	v_exp_f32_e32 v239, v117
	v_fma_f32 v68, v228, s64, v230
	v_fma_f32 v69, v228, s65, v230
	v_fma_f32 v70, v228, s66, v230
	v_fma_f32 v71, v228, s67, v230
	v_cvt_pk_bf16_f32 v98, v249, v250
	v_cvt_pk_bf16_f32 v99, v195, v251
	v_cvt_pk_bf16_f32 v100, v252, v253
	v_cvt_pk_bf16_f32 v101, v72, v73
	v_cvt_pk_bf16_f32 v114, v90, v91
	v_cvt_pk_bf16_f32 v115, v92, v93
	v_cvt_pk_bf16_f32 v116, v94, v95
	v_cvt_pk_bf16_f32 v117, v96, v97
	v_mul_f32_e32 v232, 0x42000000, v228
	v_exp_f32_e32 v240, v102
	v_exp_f32_e32 v241, v118
	v_exp_f32_e32 v242, v103
	v_exp_f32_e32 v243, v119
	ds_read_b128 v[90:93], v227 offset:53248
	s_waitcnt lgkmcnt(2)
	v_mfma_f32_32x32x16_bf16 v[18:33], v[86:89], v[74:77], v[18:33]
	v_add_f32_e32 v254, 0, v231
	v_add_f32_e32 v255, 0, v233
	v_fma_f32 v72, v228, s68, v230
	v_fma_f32 v73, v228, s69, v230
	v_exp_f32_e32 v181, v104
	v_exp_f32_e32 v183, v120
	ds_read_b128 v[86:89], v227 offset:57344
	v_mfma_f32_32x32x16_bf16 v[2:17], v[82:85], v[74:77], v[2:17]
	s_setprio 0
	v_add_f32_e32 v254, v234, v254
	v_add_f32_e32 v255, v235, v255
	v_exp_f32_e32 v195, v105
	v_exp_f32_e32 v200, v121
	ds_read_b128 v[82:85], v227 offset:61440
	s_waitcnt lgkmcnt(2)
	v_mfma_f32_32x32x16_bf16 v[50:65], v[78:81], v[98:101], v[50:65]
	v_add_f32_e32 v254, v236, v254
	v_add_f32_e32 v255, v237, v255
	v_fma_f32 v74, v228, s70, v230
	v_fma_f32 v75, v228, s71, v230
	v_exp_f32_e32 v224, v106
	v_exp_f32_e32 v122, v122
	v_add_u32_e32 v78, v198, v226
	ds_read_b128 v[94:97], v78 offset:49152
	v_mfma_f32_32x32x16_bf16 v[34:49], v[90:93], v[98:101], v[34:49]
	v_add_f32_e32 v254, v238, v254
	v_add_f32_e32 v255, v239, v255
	v_exp_f32_e32 v225, v107
	v_exp_f32_e32 v123, v123
	ds_read_b128 v[90:93], v78 offset:53248
	s_waitcnt lgkmcnt(2)
	v_mfma_f32_32x32x16_bf16 v[18:33], v[86:89], v[98:101], v[18:33]
	v_add_f32_e32 v254, v240, v254
	v_add_f32_e32 v255, v241, v255
	v_fma_f32 v76, v228, s72, v230
	v_fma_f32 v77, v228, s73, v230
	v_exp_f32_e32 v227, v108
	v_exp_f32_e32 v124, v124
	ds_read_b128 v[86:89], v78 offset:57344
	v_mfma_f32_32x32x16_bf16 v[2:17], v[82:85], v[98:101], v[2:17]
	v_add_f32_e32 v254, v242, v254
	v_add_f32_e32 v255, v243, v255
	v_exp_f32_e32 v244, v109
	v_exp_f32_e32 v125, v125
	ds_read_b128 v[98:101], v78 offset:61440
	s_waitcnt lgkmcnt(2)
	v_mfma_f32_32x32x16_bf16 v[50:65], v[94:97], v[114:117], v[50:65]
	v_add_f32_e32 v254, v181, v254
	v_add_f32_e32 v255, v183, v255
	v_fma_f32 v78, v228, s74, v230
	v_fma_f32 v79, v228, s75, v230
	v_exp_f32_e32 v245, v110
	v_exp_f32_e32 v126, v126
	v_add_u32_e32 v80, v229, v149
	ds_read_b128 v[102:105], v80
	v_mfma_f32_32x32x16_bf16 v[34:49], v[90:93], v[114:117], v[34:49]
	v_add_f32_e32 v254, v195, v254
	v_add_f32_e32 v255, v200, v255
	v_exp_f32_e32 v246, v111
	v_exp_f32_e32 v127, v127
	ds_read_b128 v[106:109], v80 offset:4096
	s_waitcnt lgkmcnt(2)
	v_mfma_f32_32x32x16_bf16 v[18:33], v[86:89], v[114:117], v[18:33]
	v_add_f32_e32 v254, v224, v254
	v_add_f32_e32 v255, v122, v255
	v_fma_f32 v80, v228, s76, v230
	v_fma_f32 v81, v228, s77, v230
	v_exp_f32_e32 v247, v112
	v_exp_f32_e32 v128, v128
	v_add_u32_e32 v110, v229, v208
	ds_read_b128 v[118:121], v110
	v_mfma_f32_32x32x16_bf16 v[2:17], v[98:101], v[114:117], v[2:17]
	v_add_f32_e32 v254, v225, v254
	v_add_f32_e32 v255, v123, v255
	v_add_f32_e64 v82, v232, v66
	v_add_f32_e64 v83, v232, v67
	v_add_f32_e64 v96, v232, v80
	v_add_f32_e64 v97, v232, v81
	v_add_f32_e64 v94, v232, v78
	v_add_f32_e64 v95, v232, v79
	v_add_f32_e32 v92, v232, v76
	v_add_f32_e32 v93, v232, v77
	v_add_f32_e32 v90, v232, v74
	v_add_f32_e32 v91, v232, v75
	v_add_f32_e32 v88, v232, v72
	v_add_f32_e32 v89, v232, v73
	v_add_f32_e32 v86, v232, v70
	v_add_f32_e32 v87, v232, v71
	v_add_f32_e32 v84, v232, v68
	v_add_f32_e32 v85, v232, v69
	v_exp_f32_e32 v228, v113
	v_exp_f32_e32 v129, v129
	ds_read_b128 v[98:101], v110 offset:4096
	s_waitcnt lgkmcnt(2)
	v_mfma_f32_32x32x16_bf16 v[66:81], v[102:105], v[130:133], v[66:81]
	v_add_f32_e32 v254, v227, v254
	v_add_f32_e32 v255, v124, v255
	v_add_f32_e32 v254, v244, v254
	v_add_u32_e32 v110, v229, v209
	ds_read_b128 v[102:105], v110
	v_mfma_f32_32x32x16_bf16 v[82:97], v[106:109], v[130:133], v[82:97]
	v_add_f32_e32 v255, v125, v255
	v_add_f32_e32 v254, v245, v254
	v_add_f32_e32 v255, v126, v255
	ds_read_b128 v[106:109], v110 offset:4096
	s_waitcnt lgkmcnt(2)
	v_mfma_f32_32x32x16_bf16 v[66:81], v[118:121], v[134:137], v[66:81]
	v_add_f32_e32 v254, v246, v254
	v_add_f32_e32 v255, v127, v255
	v_add_f32_e32 v254, v247, v254
	v_add_u32_e32 v114, v229, v226
	ds_read_b128 v[110:113], v114
	v_mfma_f32_32x32x16_bf16 v[82:97], v[98:101], v[134:137], v[82:97]
	v_add_f32_e32 v255, v128, v255
	v_add_f32_e32 v254, v228, v254
	v_add_f32_e32 v255, v129, v255
	v_add_f32_e32 v254, v255, v254
	ds_read_b128 v[98:101], v114 offset:4096
	s_waitcnt lgkmcnt(2)
	v_mfma_f32_32x32x16_bf16 v[66:81], v[102:105], v[138:141], v[66:81]
	v_cvt_pk_bf16_f32 v114, v122, v123
	v_cvt_pk_bf16_f32 v115, v124, v125
	v_cvt_pk_bf16_f32 v116, v126, v127
	v_cvt_pk_bf16_f32 v117, v128, v129
	v_mfma_f32_32x32x16_bf16 v[82:97], v[106:109], v[138:141], v[82:97]
	v_cvt_pk_bf16_f32 v106, v224, v225
	v_cvt_pk_bf16_f32 v107, v227, v244
	v_cvt_pk_bf16_f32 v108, v245, v246
	v_cvt_pk_bf16_f32 v109, v247, v228
	s_waitcnt lgkmcnt(0)
	v_mfma_f32_32x32x16_bf16 v[66:81], v[110:113], v[142:145], v[66:81]
	v_cvt_pk_bf16_f32 v110, v233, v235
	v_cvt_pk_bf16_f32 v111, v237, v239
	v_cvt_pk_bf16_f32 v112, v241, v243
	v_cvt_pk_bf16_f32 v113, v183, v200
	v_mfma_f32_32x32x16_bf16 v[82:97], v[98:101], v[142:145], v[82:97]
	s_add_i32 s10, s4, 1
	s_cmp_lg_u32 s4, 2
	s_cselect_b32 s62, s10, 0
	s_add_i32 s4, s5, 1
	s_cmp_lg_u32 s5, 2
	s_cselect_b32 s10, s4, 0
	s_add_i32 s34, s34, 2
	v_add_f32_e32 v198, v179, v254
	v_cvt_pk_bf16_f32 v98, v231, v234
	v_cvt_pk_bf16_f32 v99, v236, v238
	v_cvt_pk_bf16_f32 v100, v240, v242
	v_cvt_pk_bf16_f32 v101, v181, v195
	s_cmp_ge_i32 s61, s48
	s_cbranch_scc1 .LBB0_473
	s_mov_b32 s60, s63
	s_add_i32 s61, s34, -2
	s_cmp_gt_i32 s61, s48
	s_cbranch_scc1 .LBB0_469
